# v26 + prep w_gate_up transpose loop: the loop-top vmcnt(0) (which also waited for the previous tile's write-through stores) moved in front of the loop
# baseline (speedup 1.0000x reference)
.LBB0_37:
	s_add_u32 s20, s88, 0xd00000
	s_addc_u32 s21, s89, 0
	s_cmpk_lt_i32 s24, 0x1000
	v_mov_b32_e32 v30, v128
	s_cselect_b64 s[2:3], -1, 0
	s_cmpk_gt_i32 s24, 0xfff
	s_cbranch_scc1 .LBB0_40
	s_ashr_i32 s0, s24, 31
	s_lshr_b32 s0, s0, 25
	s_add_i32 s4, s24, s0
	s_ashr_i32 s0, s4, 7
	s_ashr_i32 s1, s0, 31
	s_lshl_b64 s[0:1], s[0:1], 21
	s_waitcnt lgkmcnt(0)
	s_add_u32 s5, s74, s0
	s_addc_u32 s6, s75, s1
	s_and_b32 s0, s4, 0xffffff80
	s_sub_i32 s4, s24, s0
	s_ashr_i32 s0, s4, 31
	s_lshr_b32 s0, s0, 29
	s_add_i32 s0, s4, s0
	s_ashr_i32 s7, s0, 3
	s_lshl_b32 s0, s7, 6
	s_ashr_i32 s1, s0, 31
	s_lshl_b64 s[0:1], s[0:1], 11
	s_add_u32 s5, s5, s0
	s_addc_u32 s6, s6, s1
	s_lshl_b32 s0, s7, 9
	s_lshl_b32 s1, s4, 6
	s_sub_i32 s0, s1, s0
	s_ashr_i32 s1, s0, 31
	v_ashrrev_i32_e32 v28, 4, v30
	s_lshl_b64 s[0:1], s[0:1], 2
	v_and_b32_e32 v1, 15, v30
	v_add_u32_e32 v22, 16, v28
	v_add_u32_e32 v24, 32, v28
	v_add_u32_e32 v26, 48, v28
	s_add_u32 s0, s5, s0
	v_mov_b32_e32 v19, 0
	v_ashrrev_i32_e32 v29, 31, v28
	v_ashrrev_i32_e32 v23, 31, v22
	v_ashrrev_i32_e32 v25, 31, v24
	v_ashrrev_i32_e32 v27, 31, v26
	s_addc_u32 s1, s6, s1
	v_lshlrev_b32_e32 v18, 4, v1
	v_lshl_add_u64 v[10:11], s[0:1], 0, v[18:19]
	v_lshlrev_b64 v[2:3], 11, v[26:27]
	v_lshlrev_b64 v[4:5], 11, v[24:25]
	v_lshlrev_b64 v[12:13], 11, v[22:23]
	v_lshlrev_b64 v[14:15], 11, v[28:29]
	v_lshl_add_u64 v[2:3], v[10:11], 0, v[2:3]
	v_lshl_add_u64 v[6:7], v[10:11], 0, v[4:5]
	v_lshl_add_u64 v[12:13], v[10:11], 0, v[12:13]
	v_lshl_add_u64 v[14:15], v[10:11], 0, v[14:15]
	global_load_dwordx4 v[2:5], v[2:3], off nt
	s_nop 0
	global_load_dwordx4 v[6:9], v[6:7], off nt
	s_nop 0
	global_load_dwordx4 v[10:13], v[12:13], off nt
	s_nop 0
	global_load_dwordx4 v[14:17], v[14:15], off nt
	v_lshlrev_b32_e32 v18, 2, v1
	v_mul_u32_u24_e32 v1, 0x120, v1
	v_lshlrev_b32_e32 v1, 1, v1
	v_lshlrev_b64 v[20:21], 9, v[28:29]
	v_lshl_add_u32 v1, v28, 1, v1
	v_lshlrev_b32_e32 v28, 3, v30
	v_and_b32_e32 v32, 56, v28
	v_lshlrev_b32_e32 v36, 1, v32
	v_ashrrev_i32_e32 v34, 3, v30
	s_movk_i32 s5, 0x90
	v_mad_u64_u32 v[28:29], s[0:1], v34, s5, v[36:37]
	v_add_u32_e32 v29, 0x100, v30
	v_ashrrev_i32_e32 v29, 3, v29
	v_mad_u64_u32 v[30:31], s[0:1], v29, s5, v[36:37]
	v_lshlrev_b64 v[22:23], 9, v[22:23]
	v_lshlrev_b64 v[24:25], 9, v[24:25]
	v_lshlrev_b64 v[26:27], 9, v[26:27]
	s_movk_i32 s4, 0x100
	v_and_b32_e32 v31, 31, v34
	v_and_b32_e32 v35, 31, v29
	s_lshl_b32 s5, s24, 6
	s_lshl_b32 s6, s90, 6
	v_lshlrev_b32_e32 v18, 2, v18
	v_lshlrev_b32_e32 v32, 1, v32
	v_mov_b32_e32 v33, v19
	v_mov_b32_e32 v36, 0xffffff00
	s_mov_b32 s14, s24
	s_waitcnt vmcnt(0)
.LBB0_39:
	s_ashr_i32 s0, s14, 31
	v_cvt_pk_bf16_f32 v37, v14, s0
	v_cvt_pk_bf16_f32 v42, v15, s0
	v_cvt_pk_bf16_f32 v43, v16, s0
	v_cvt_pk_bf16_f32 v44, v17, s0
	v_cvt_pk_bf16_f32 v45, v10, s0
	v_cvt_pk_bf16_f32 v46, v11, s0
	v_cvt_pk_bf16_f32 v47, v12, s0
	v_cvt_pk_bf16_f32 v48, v13, s0
	v_cvt_pk_bf16_f32 v49, v6, s0
	v_cvt_pk_bf16_f32 v50, v7, s0
	v_cvt_pk_bf16_f32 v51, v8, s0
	v_cvt_pk_bf16_f32 v52, v9, s0
	s_lshr_b32 s0, s0, 25
	s_add_i32 s1, s14, s0
	s_ashr_i32 s0, s1, 7
	s_and_b32 s1, s1, 0xffffff80
	s_sub_i32 s1, s14, s1
	s_ashr_i32 s15, s1, 31
	s_lshr_b32 s15, s15, 29
	s_add_i32 s1, s1, s15
	s_add_i32 s7, s14, s90
	s_ashr_i32 s18, s1, 3
	s_cmpk_lt_u32 s7, 0x1000
	s_cselect_b32 s1, s7, s14
	s_ashr_i32 s14, s1, 31
	s_lshr_b32 s14, s14, 25
	s_add_i32 s15, s1, s14
	s_ashr_i32 s14, s15, 7
	s_and_b32 s15, s15, 0xffffff80
	s_sub_i32 s1, s1, s15
	s_ashr_i32 s16, s1, 31
	s_lshr_b32 s16, s16, 29
	s_ashr_i32 s15, s14, 31
	s_add_i32 s16, s1, s16
	s_lshl_b64 s[14:15], s[14:15], 21
	s_ashr_i32 s16, s16, 3
	s_add_u32 s17, s74, s14
	s_addc_u32 s19, s75, s15
	s_lshl_b32 s14, s16, 6
	s_ashr_i32 s15, s14, 31
	s_lshl_b64 s[14:15], s[14:15], 11
	s_add_u32 s17, s17, s14
	s_addc_u32 s19, s19, s15
	s_lshl_b32 s14, s16, 9
	s_lshl_b32 s1, s1, 6
	s_sub_i32 s14, s1, s14
	s_ashr_i32 s15, s14, 31
	s_lshl_b64 s[14:15], s[14:15], 2
	s_add_u32 s14, s17, s14
	s_addc_u32 s15, s19, s15
	v_lshl_add_u64 v[6:7], s[14:15], 0, v[18:19]
	v_lshl_add_u64 v[8:9], v[20:21], 2, v[6:7]
	v_lshl_add_u64 v[10:11], v[22:23], 2, v[6:7]
	v_lshl_add_u64 v[38:39], v[24:25], 2, v[6:7]
	v_lshl_add_u64 v[40:41], v[26:27], 2, v[6:7]
	global_load_dwordx4 v[14:17], v[8:9], off nt
	s_nop 0
	global_load_dwordx4 v[10:13], v[10:11], off nt
	s_nop 0
	global_load_dwordx4 v[6:9], v[38:39], off nt
	s_nop 0
	global_load_dwordx4 v[38:41], v[40:41], off nt
	s_ashr_i32 s1, s0, 31
	s_lshl_b64 s[16:17], s[0:1], 20
	s_add_u32 s1, s20, s16
	s_addc_u32 s15, s21, s17
	s_lshl_b32 s16, s18, 6
	s_ashr_i32 s17, s16, 31
	s_lshl_b32 s19, s18, 9
	s_lshl_b64 s[16:17], s[16:17], 1
	s_add_u32 s16, s1, s16
	s_addc_u32 s17, s15, s17
	s_lshl_b32 s15, s0, 13
	v_cvt_pk_bf16_f32 v2, v2, s0
	v_cvt_pk_bf16_f32 v3, v3, s0
	v_cvt_pk_bf16_f32 v4, v4, s0
	v_cvt_pk_bf16_f32 v5, v5, s0
	v_add_u32_e32 v53, s5, v34
	s_add_i32 s0, s19, s15
	v_add_u32_e32 v54, s5, v29
	s_barrier
	ds_write_b16 v1, v37
	ds_write_b16 v1, v42 offset:144
	ds_write_b16 v1, v43 offset:288
	ds_write_b16 v1, v44 offset:432
	ds_write_b16 v1, v45 offset:32
	ds_write_b16 v1, v46 offset:176
	ds_write_b16 v1, v47 offset:320
	ds_write_b16 v1, v48 offset:464
	ds_write_b16 v1, v49 offset:64
	ds_write_b16 v1, v50 offset:208
	ds_write_b16 v1, v51 offset:352
	ds_write_b16 v1, v52 offset:496
	ds_write_b16 v1, v2 offset:96
	ds_write_b16 v1, v3 offset:240
	ds_write_b16 v1, v4 offset:384
	ds_write_b16 v1, v5 offset:528
	v_subrev_u32_e32 v37, s0, v53
	v_subrev_u32_e32 v48, s0, v54
	v_cmp_gt_i32_e32 vcc, s4, v37
	v_cmp_gt_i32_e64 s[0:1], s4, v48
	s_waitcnt lgkmcnt(0)
	v_cndmask_b32_e64 v37, v36, 0, vcc
	v_cndmask_b32_e64 v48, v36, 0, s[0:1]
	v_subrev_u32_e32 v37, s19, v37
	v_subrev_u32_e32 v48, s19, v48
	v_subrev_u32_e32 v37, s15, v37
	v_subrev_u32_e32 v48, s15, v48
	v_add_lshl_u32 v37, v53, v37, 1
	s_barrier
	ds_read_b128 v[2:5], v28
	ds_read_b128 v[42:45], v30
	v_cndmask_b32_e64 v49, 32, 0, vcc
	v_add_lshl_u32 v48, v54, v48, 1
	v_and_b32_e32 v37, 0xffffffc0, v37
	v_cndmask_b32_e64 v50, 32, 0, s[0:1]
	v_and_b32_e32 v51, 0xffffffc0, v48
	v_or3_b32 v48, v49, v31, v37
	v_or3_b32 v50, v50, v35, v51
	v_ashrrev_i32_e32 v49, 31, v48
	v_lshl_add_u64 v[46:47], s[16:17], 0, v[32:33]
	v_ashrrev_i32_e32 v51, 31, v50
	v_lshlrev_b64 v[48:49], 11, v[48:49]
	s_add_i32 s5, s5, s6
	v_lshlrev_b64 v[50:51], 11, v[50:51]
	v_lshl_add_u64 v[48:49], v[46:47], 0, v[48:49]
	s_mov_b32 s14, s7
	s_cmpk_lt_i32 s7, 0x1000
	v_lshl_add_u64 v[46:47], v[46:47], 0, v[50:51]
	s_waitcnt lgkmcnt(1)
	global_store_dwordx4 v[48:49], v[2:5], off sc0 sc1
	s_waitcnt lgkmcnt(0)
	global_store_dwordx4 v[46:47], v[42:45], off sc0 sc1
	s_waitcnt vmcnt(2)
	v_mov_b64_e32 v[2:3], v[38:39]
	v_mov_b64_e32 v[4:5], v[40:41]
	s_cbranch_scc1 .LBB0_39
